# v34 + SW attention output stores widened to dwordx4 (permlane32_swap pairs)
# baseline (speedup 1.0000x reference)
; __device__ __forceinline__ void sw_attn(const bf16* QKV, const float* rope, const float* qg, const float* kg, const float* sinks, bf16* O, LAS unsigned char* lds, int tid) {
;     ...
;             for (int js = 0; js < 5; ++js) {
; #pragma unroll
;                 for (int r = 0; r < 16; ++r) s[js][r] = 0.f;
;                 const bool live = !(blk == 0 && tb + js < 4);
;                 if (live) {
; #pragma unroll
;                     for (int ks = 0; ks < 4; ++ks) { const bf16x8 a = *(const LAS bf16x8*)(kl + (32 * (tb + js) + l32) * KROW + 32 * ks + 16 * hi); s[js] = SB_MFMA(a, qf[ks], s[js]); }
; #pragma unroll
;                     for (int r = 0; r < 16; ++r) {
;                         const int kk = (r & 3) + 8 * (r >> 2) + 4 * hi;
;                         float v = s[js][r];
;                         if (js == 0) v = (kk > l32) ? v : NEG;
;                         if (js == 4) v = (kk <= l32) ? v : NEG;
;                         s[js][r] = v; mx = fmaxf(mx, v);
;                     }
;                 } else {
; #pragma unroll
;                     for (int r = 0; r < 16; ++r) s[js][r] = NEG;
;                 }
;                 asm volatile("" ::: "memory");
;             }
;             { float lo_, up_; halves(mx, lo_, up_); mx = fmaxf(lo_, up_); }
;             float l = 0.f;
;             f32x16 o0, o1;
; #pragma unroll
;             for (int r = 0; r < 16; ++r) { o0[r] = 0.f; o1[r] = 0.f; }
; #pragma unroll
;             for (int js = 0; js < 5; ++js) {
;                 unsigned pw[8];
; #pragma unroll
;                 for (int r = 0; r < 16; r += 2) { const float p0 = __builtin_amdgcn_exp2f(s[js][r] - mx), p1 = __builtin_amdgcn_exp2f(s[js][r + 1] - mx); l += p0 + p1; pw[r >> 1] = cvtpk(p0, p1); }
; #pragma unroll
;                 for (int kk = 0; kk < 2; ++kk) {
;                     const v4u pv = {pw[4 * kk], pw[4 * kk + 1], pw[4 * kk + 2], pw[4 * kk + 3]};
;                     const bf16x8 pb = __builtin_bit_cast(bf16x8, pv);
; #pragma unroll
;                     for (int dh = 0; dh < 2; ++dh) {
;                         const LAS unsigned char* vp = vl + (32 * dh + l32) * VROW + (32 * (tb + js) + 16 * kk + 4 * hi) * 2;
;                         const u32x2 lo = *(const LAS u32x2*)vp, hi2 = *(const LAS u32x2*)(vp + 16);
;                         const v4u av = {lo[0], lo[1], hi2[0], hi2[1]};
.LBB0_173:
	ds_read_b128 v[22:25], v138
	ds_read_b128 v[146:149], v138 offset:32
	v_add_u32_e32 v195, 0xd000, v139
	s_lshl_b32 s18, s18, 6
	s_ashr_i32 s19, s18, 31
	s_waitcnt lgkmcnt(1)
	v_mfma_f32_32x32x16_bf16 v[16:31], v[22:25], v[18:21], 0
	s_add_i32 s34, s34, 8
	s_cmp_eq_u32 s34, 32
	s_waitcnt lgkmcnt(0)
	v_mfma_f32_32x32x16_bf16 v[16:31], v[146:149], v[36:39], v[16:31]
	ds_read_b128 v[36:39], v138 offset:64
	ds_read_b128 v[146:149], v138 offset:96
	s_waitcnt lgkmcnt(1)
	v_mfma_f32_32x32x16_bf16 v[16:31], v[36:39], v[40:43], v[16:31]
	v_add_u32_e32 v40, 0x9000, v139
	s_waitcnt lgkmcnt(0)
	v_mfma_f32_32x32x16_bf16 v[16:31], v[146:149], v[32:35], v[16:31]
	s_nop 11
	v_cndmask_b32_e64 v172, v16, v234, s[42:43]
	v_cndmask_b32_e64 v171, v234, v17, s[44:45]
	v_cndmask_b32_e64 v170, v18, v234, s[46:47]
	v_cndmask_b32_e64 v169, v19, v234, s[48:49]
	v_max3_f32 v16, v144, v172, v171
	v_cndmask_b32_e64 v158, v20, v234, s[50:51]
	v_cndmask_b32_e64 v155, v21, v234, s[52:53]
	v_max3_f32 v16, v16, v170, v169
	v_cndmask_b32_e64 v154, v22, v234, s[54:55]
	v_cndmask_b32_e64 v153, v23, v234, s[56:57]
	v_max3_f32 v16, v16, v158, v155
	v_cndmask_b32_e64 v152, v24, v234, s[58:59]
	v_cndmask_b32_e64 v151, v25, v234, s[60:61]
	v_max3_f32 v16, v16, v154, v153
	v_cndmask_b32_e64 v150, v26, v234, s[62:63]
	v_cndmask_b32_e64 v149, v27, v234, s[64:65]
	v_max3_f32 v16, v16, v152, v151
	v_cndmask_b32_e64 v148, v28, v234, s[66:67]
	v_cndmask_b32_e64 v147, v29, v234, s[68:69]
	v_max3_f32 v16, v16, v150, v149
	v_cndmask_b32_e64 v146, v30, v234, s[70:71]
	v_cndmask_b32_e64 v145, v31, v234, s[72:73]
	v_max3_f32 v16, v16, v148, v147
	v_max3_f32 v16, v16, v146, v145
	v_mov_b32_e32 v17, v16
	ds_read2_b64 v[36:39], v195 offset0:32 offset1:34
	s_nop 0
	v_permlane32_swap_b32_e32 v16, v17
	v_max_f32_e32 v17, v17, v17
	v_max_f32_e32 v16, v16, v16
	v_max_f32_e32 v144, v16, v17
	v_sub_f32_e32 v16, v182, v144
	v_sub_f32_e32 v17, v183, v144
	v_sub_f32_e32 v18, v178, v144
	v_sub_f32_e32 v19, v179, v144
	v_sub_f32_e32 v22, v156, v144
	v_exp_f32_e32 v183, v16
	v_exp_f32_e32 v185, v17
	v_exp_f32_e32 v182, v18
	v_exp_f32_e32 v156, v19
	ds_read2_b64 v[16:19], v40 offset1:2
	v_sub_f32_e32 v20, v180, v144
	v_sub_f32_e32 v21, v181, v144
	v_sub_f32_e32 v23, v176, v144
	v_exp_f32_e32 v187, v20
	v_exp_f32_e32 v189, v21
	v_exp_f32_e32 v184, v22
	v_exp_f32_e32 v186, v23
	v_sub_f32_e32 v20, v47, v144
	v_sub_f32_e32 v24, v177, v144
	v_cvt_pk_bf16_f32 v32, v183, v185
	v_cvt_pk_bf16_f32 v33, v182, v156
	v_cvt_pk_bf16_f32 v34, v187, v189
	v_cvt_pk_bf16_f32 v35, v184, v186
	v_exp_f32_e32 v193, v20
	v_sub_f32_e32 v20, v174, v144
	v_sub_f32_e32 v41, v175, v144
	ds_read2_b64 v[174:177], v40 offset0:4 offset1:6
	v_exp_f32_e32 v191, v24
	v_exp_f32_e32 v188, v20
	s_waitcnt lgkmcnt(1)
	v_mfma_f32_32x32x16_bf16 v[16:31], v[16:19], v[32:35], 0
	v_exp_f32_e32 v190, v41
	v_sub_f32_e32 v41, v44, v144
	v_exp_f32_e32 v196, v41
	v_sub_f32_e32 v41, v45, v144
	v_sub_f32_e32 v178, v46, v144
	v_sub_f32_e32 v173, v173, v144
	v_exp_f32_e32 v197, v41
	v_exp_f32_e32 v192, v178
	v_exp_f32_e32 v194, v173
	v_cvt_pk_bf16_f32 v178, v191, v193
	v_cvt_pk_bf16_f32 v179, v188, v190
	v_cvt_pk_bf16_f32 v180, v196, v197
	v_cvt_pk_bf16_f32 v181, v192, v194
	v_mfma_f32_32x32x16_bf16 v[32:47], v[36:39], v[32:35], 0
	v_add_f32_e32 v183, v183, v185
	v_add_f32_e32 v185, v187, v189
	v_add_f32_e32 v189, v191, v193
	v_sub_f32_e32 v0, v0, v144
	v_add_f32_e32 v193, v196, v197
	v_sub_f32_e32 v8, v8, v144
	v_sub_f32_e32 v14, v14, v144
	s_waitcnt lgkmcnt(0)
	v_mfma_f32_32x32x16_bf16 v[16:31], v[174:177], v[178:181], v[16:31]
	ds_read2_b64 v[174:177], v195 offset0:36 offset1:38
	s_waitcnt lgkmcnt(0)
	v_mfma_f32_32x32x16_bf16 v[32:47], v[174:177], v[178:181], v[32:47]
	v_add_f32_e64 v174, v182, v156
	v_add_f32_e64 v175, v183, v157
	v_exp_f32_e32 v156, v0
	v_pk_add_f32 v[174:175], v[174:175], v[174:175] op_sel_hi:[0,1]
	v_mov_b32_e32 v187, v175
	v_pk_add_f32 v[174:175], v[184:185], v[186:187]
	v_sub_f32_e32 v0, v1, v144
	v_pk_add_f32 v[174:175], v[174:175], v[174:175] op_sel_hi:[0,1]
	v_mov_b32_e32 v191, v175
	v_pk_add_f32 v[174:175], v[188:189], v[190:191]
	v_exp_f32_e32 v173, v0
	v_pk_add_f32 v[174:175], v[174:175], v[174:175] op_sel_hi:[0,1]
	v_mov_b32_e32 v195, v175
	v_pk_add_f32 v[174:175], v[192:193], v[194:195]
	v_sub_f32_e32 v0, v2, v144
	v_pk_add_f32 v[174:175], v[174:175], v[174:175] op_sel_hi:[0,1]
	v_exp_f32_e32 v176, v0
	v_sub_f32_e32 v0, v3, v144
	v_exp_f32_e32 v174, v0
	v_sub_f32_e32 v0, v4, v144
	v_exp_f32_e32 v179, v0
	v_sub_f32_e32 v0, v5, v144
	v_exp_f32_e32 v181, v0
	v_sub_f32_e32 v0, v6, v144
	v_add_u32_e32 v177, 0x9000, v140
	v_exp_f32_e32 v178, v0
	v_sub_f32_e32 v0, v7, v144
	ds_read2_b64 v[4:7], v177 offset1:2
	v_exp_f32_e32 v183, v8
	v_sub_f32_e32 v8, v9, v144
	v_exp_f32_e32 v180, v0
	v_exp_f32_e32 v185, v8
	v_sub_f32_e32 v8, v10, v144
	v_add_u32_e32 v186, 0xd000, v140
	v_exp_f32_e32 v182, v8
	v_sub_f32_e32 v184, v11, v144
	ds_read2_b64 v[8:11], v186 offset0:32 offset1:34
	v_cvt_pk_bf16_f32 v0, v156, v173
	v_cvt_pk_bf16_f32 v1, v176, v174
	v_cvt_pk_bf16_f32 v2, v179, v181
	v_cvt_pk_bf16_f32 v3, v178, v180
	v_exp_f32_e32 v184, v184
	v_add_f32_e32 v179, v179, v181
	s_waitcnt lgkmcnt(1)
	v_mfma_f32_32x32x16_bf16 v[16:31], v[4:7], v[0:3], v[16:31]
	v_sub_f32_e32 v4, v12, v144
	v_exp_f32_e32 v12, v4
	v_sub_f32_e32 v4, v13, v144
	v_exp_f32_e32 v13, v4
	ds_read2_b64 v[4:7], v177 offset0:4 offset1:6
	v_add_f32_e32 v177, v156, v173
	s_waitcnt lgkmcnt(1)
	v_mfma_f32_32x32x16_bf16 v[32:47], v[8:11], v[0:3], v[32:47]
	v_sub_f32_e32 v0, v15, v144
	v_exp_f32_e32 v8, v14
	v_exp_f32_e32 v10, v0
	v_cvt_pk_bf16_f32 v0, v183, v185
	v_cvt_pk_bf16_f32 v1, v182, v184
	v_cvt_pk_bf16_f32 v2, v12, v13
	v_cvt_pk_bf16_f32 v3, v8, v10
	v_add_f32_e32 v183, v183, v185
	v_add_f32_e32 v9, v12, v13
	s_waitcnt lgkmcnt(0)
; #define LAS __attribute__((address_space(3)))
; __device__ __forceinline__ unsigned cvtpk(float lo, float hi) { f32x2_t v = {lo, hi}; bf16x2_t b = __builtin_convertvector(v, bf16x2_t); return __builtin_bit_cast(unsigned, b); }
; #define SB_MFMA(a, b, c) __builtin_amdgcn_mfma_f32_32x32x16_bf16((a), (b), (c), 0, 0, 0)
; __device__ __forceinline__ void sw_attn(const bf16* QKV, const float* rope, const float* qg, const float* kg, const float* sinks, bf16* O, LAS unsigned char* lds, int tid) {
;     ...
;             for (int js = 0; js < 5; ++js) {
;                 unsigned pw[8];
; #pragma unroll
;                 for (int r = 0; r < 16; r += 2) { const float p0 = __builtin_amdgcn_exp2f(s[js][r] - mx), p1 = __builtin_amdgcn_exp2f(s[js][r + 1] - mx); l += p0 + p1; pw[r >> 1] = cvtpk(p0, p1); }
; #pragma unroll
;                 for (int kk = 0; kk < 2; ++kk) {
;                     const v4u pv = {pw[4 * kk], pw[4 * kk + 1], pw[4 * kk + 2], pw[4 * kk + 3]};
;                     const bf16x8 pb = __builtin_bit_cast(bf16x8, pv);
; #pragma unroll
;                     for (int dh = 0; dh < 2; ++dh) {
;                         const LAS unsigned char* vp = vl + (32 * dh + l32) * VROW + (32 * (tb + js) + 16 * kk + 4 * hi) * 2;
;                         const u32x2 lo = *(const LAS u32x2*)vp, hi2 = *(const LAS u32x2*)(vp + 16);
;                         const v4u av = {lo[0], lo[1], hi2[0], hi2[1]};
;                         const bf16x8 a = __builtin_bit_cast(bf16x8, av);
;                         if (dh == 0) o0 = SB_MFMA(a, pb, o0); else o1 = SB_MFMA(a, pb, o1);
;                     }
;                 }
;                 asm volatile("" ::: "memory");
;             }
	v_mfma_f32_32x32x16_bf16 v[16:31], v[4:7], v[0:3], v[16:31]
	ds_read2_b64 v[4:7], v186 offset0:36 offset1:38
	s_waitcnt lgkmcnt(0)
	v_mfma_f32_32x32x16_bf16 v[32:47], v[4:7], v[0:3], v[32:47]
	v_add_f32_e64 v0, v176, v174
	v_add_f32_e64 v1, v177, v175
	v_pk_add_f32 v[0:1], v[0:1], v[0:1] op_sel_hi:[0,1]
	v_mov_b32_e32 v181, v1
	v_pk_add_f32 v[0:1], v[178:179], v[180:181]
	s_nop 0
	v_pk_add_f32 v[0:1], v[0:1], v[0:1] op_sel_hi:[0,1]
	v_mov_b32_e32 v185, v1
	v_pk_add_f32 v[0:1], v[182:183], v[184:185]
	s_nop 0
	v_pk_add_f32 v[0:1], v[0:1], v[0:1] op_sel_hi:[0,1]
	v_mov_b32_e32 v11, v1
	v_pk_add_f32 v[0:1], v[8:9], v[10:11]
	v_sub_f32_e32 v8, v72, v144
	v_pk_add_f32 v[12:13], v[0:1], v[0:1] op_sel_hi:[0,1]
	v_sub_f32_e32 v0, v64, v144
	v_exp_f32_e32 v15, v0
	v_sub_f32_e32 v0, v65, v144
	v_exp_f32_e32 v65, v0
	v_sub_f32_e32 v0, v66, v144
	v_exp_f32_e32 v14, v0
	v_sub_f32_e32 v0, v67, v144
	v_exp_f32_e32 v12, v0
	v_sub_f32_e32 v0, v68, v144
	v_exp_f32_e32 v67, v0
	v_sub_f32_e32 v0, v69, v144
	v_exp_f32_e32 v69, v0
	v_sub_f32_e32 v0, v70, v144
	v_exp_f32_e32 v64, v0
	v_sub_f32_e32 v0, v71, v144
	v_add_u32_e32 v71, 0x9000, v141
	ds_read2_b64 v[4:7], v71 offset1:2
	v_exp_f32_e32 v72, v8
	v_sub_f32_e32 v8, v73, v144
	v_exp_f32_e32 v66, v0
	v_exp_f32_e32 v73, v8
	v_sub_f32_e32 v8, v74, v144
	v_add_u32_e32 v74, 0xd000, v141
	v_exp_f32_e32 v68, v8
	ds_read2_b64 v[8:11], v74 offset0:32 offset1:34
	v_cvt_pk_bf16_f32 v0, v15, v65
	v_cvt_pk_bf16_f32 v1, v14, v12
	v_cvt_pk_bf16_f32 v2, v67, v69
	v_cvt_pk_bf16_f32 v3, v64, v66
	v_sub_f32_e32 v70, v75, v144
	v_exp_f32_e32 v70, v70
	s_waitcnt lgkmcnt(1)
	v_mfma_f32_32x32x16_bf16 v[16:31], v[4:7], v[0:3], v[16:31]
	v_sub_f32_e32 v4, v76, v144
	v_exp_f32_e32 v75, v4
	v_sub_f32_e32 v4, v77, v144
	v_exp_f32_e32 v76, v4
	ds_read2_b64 v[4:7], v71 offset0:4 offset1:6
	v_sub_f32_e32 v77, v78, v144
	v_add_f32_e32 v15, v15, v65
	s_waitcnt lgkmcnt(1)
	v_mfma_f32_32x32x16_bf16 v[32:47], v[8:11], v[0:3], v[32:47]
	v_sub_f32_e32 v0, v79, v144
	v_exp_f32_e32 v8, v77
	v_exp_f32_e32 v10, v0
	v_cvt_pk_bf16_f32 v0, v72, v73
	v_cvt_pk_bf16_f32 v1, v68, v70
	v_cvt_pk_bf16_f32 v2, v75, v76
	v_cvt_pk_bf16_f32 v3, v8, v10
	v_add_f32_e32 v65, v67, v69
	v_add_f32_e32 v69, v72, v73
	s_waitcnt lgkmcnt(0)
	v_mfma_f32_32x32x16_bf16 v[16:31], v[4:7], v[0:3], v[16:31]
	ds_read2_b64 v[4:7], v74 offset0:36 offset1:38
	v_add_f32_e32 v9, v75, v76
	s_waitcnt lgkmcnt(0)
	v_mfma_f32_32x32x16_bf16 v[32:47], v[4:7], v[0:3], v[32:47]
	v_add_f32_e64 v0, v14, v12
	v_add_f32_e64 v1, v15, v13
	v_pk_add_f32 v[0:1], v[0:1], v[0:1] op_sel_hi:[0,1]
	v_mov_b32_e32 v67, v1
	v_pk_add_f32 v[0:1], v[64:65], v[66:67]
	s_nop 0
	v_pk_add_f32 v[0:1], v[0:1], v[0:1] op_sel_hi:[0,1]
	v_mov_b32_e32 v71, v1
	v_pk_add_f32 v[0:1], v[68:69], v[70:71]
	s_nop 0
	v_pk_add_f32 v[0:1], v[0:1], v[0:1] op_sel_hi:[0,1]
	v_mov_b32_e32 v11, v1
	v_pk_add_f32 v[0:1], v[8:9], v[10:11]
	v_sub_f32_e32 v8, v56, v144
	v_pk_add_f32 v[12:13], v[0:1], v[0:1] op_sel_hi:[0,1]
	v_sub_f32_e32 v0, v48, v144
	v_exp_f32_e32 v15, v0
	v_sub_f32_e32 v0, v49, v144
	v_exp_f32_e32 v49, v0
	v_sub_f32_e32 v0, v50, v144
	v_exp_f32_e32 v14, v0
	v_sub_f32_e32 v0, v51, v144
	v_exp_f32_e32 v12, v0
	v_sub_f32_e32 v0, v52, v144
	v_exp_f32_e32 v51, v0
	v_sub_f32_e32 v0, v53, v144
	v_exp_f32_e32 v53, v0
	v_sub_f32_e32 v0, v54, v144
	v_exp_f32_e32 v48, v0
	v_sub_f32_e32 v0, v55, v144
	v_add_u32_e32 v55, 0x9000, v142
	ds_read2_b64 v[4:7], v55 offset1:2
	v_exp_f32_e32 v56, v8
	v_sub_f32_e32 v8, v57, v144
	v_exp_f32_e32 v50, v0
	v_exp_f32_e32 v57, v8
	v_sub_f32_e32 v8, v58, v144
	v_add_u32_e32 v58, 0xd000, v142
	v_exp_f32_e32 v52, v8
	ds_read2_b64 v[8:11], v58 offset0:32 offset1:34
	v_cvt_pk_bf16_f32 v0, v15, v49
	v_cvt_pk_bf16_f32 v1, v14, v12
	v_cvt_pk_bf16_f32 v2, v51, v53
	v_cvt_pk_bf16_f32 v3, v48, v50
	v_sub_f32_e32 v54, v59, v144
	v_exp_f32_e32 v54, v54
	s_waitcnt lgkmcnt(1)
	v_mfma_f32_32x32x16_bf16 v[16:31], v[4:7], v[0:3], v[16:31]
	v_sub_f32_e32 v4, v60, v144
	v_exp_f32_e32 v59, v4
	v_sub_f32_e32 v4, v61, v144
	v_exp_f32_e32 v60, v4
	ds_read2_b64 v[4:7], v55 offset0:4 offset1:6
	v_sub_f32_e32 v61, v62, v144
	v_add_f32_e32 v15, v15, v49
	s_waitcnt lgkmcnt(1)
	v_mfma_f32_32x32x16_bf16 v[32:47], v[8:11], v[0:3], v[32:47]
	v_sub_f32_e32 v0, v63, v144
	v_exp_f32_e32 v8, v61
	v_exp_f32_e32 v10, v0
	v_cvt_pk_bf16_f32 v0, v56, v57
	v_cvt_pk_bf16_f32 v1, v52, v54
	v_cvt_pk_bf16_f32 v2, v59, v60
	v_cvt_pk_bf16_f32 v3, v8, v10
	v_add_f32_e32 v49, v51, v53
	v_add_f32_e32 v53, v56, v57
	s_waitcnt lgkmcnt(0)
	v_mfma_f32_32x32x16_bf16 v[16:31], v[4:7], v[0:3], v[16:31]
	ds_read2_b64 v[4:7], v58 offset0:36 offset1:38
	v_add_f32_e32 v9, v59, v60
	v_add_u32_e32 v57, 0xd000, v143
	s_waitcnt lgkmcnt(0)
; __device__ __forceinline__ unsigned cvtpk(float lo, float hi) { f32x2_t v = {lo, hi}; bf16x2_t b = __builtin_convertvector(v, bf16x2_t); return __builtin_bit_cast(unsigned, b); }
; __device__ __forceinline__ void sw_attn(const bf16* QKV, const float* rope, const float* qg, const float* kg, const float* sinks, bf16* O, LAS unsigned char* lds, int tid) {
;     ...
;             { float lo_, up_; halves(l, lo_, up_); l = lo_ + up_; }
;             l += __builtin_amdgcn_exp2f(sink - mx);
;             const float il = 1.0f / l;
;             bf16* op = O + qrow * D + hq * 64 + 4 * hi;
; #pragma unroll
;             for (int gg = 0; gg < 4; ++gg) {
;                 const u32x2 a = {cvtpk(o0[4 * gg] * il, o0[4 * gg + 1] * il), cvtpk(o0[4 * gg + 2] * il, o0[4 * gg + 3] * il)}, c = {cvtpk(o1[4 * gg] * il, o1[4 * gg + 1] * il), cvtpk(o1[4 * gg + 2] * il, o1[4 * gg + 3] * il)};
;                 *(u32x2*)(op + 8 * gg) = a; *(u32x2*)(op + 32 + 8 * gg) = c; }
	v_mfma_f32_32x32x16_bf16 v[32:47], v[4:7], v[0:3], v[32:47]
	v_add_f32_e64 v0, v14, v12
	v_add_f32_e64 v1, v15, v13
	v_sub_f32_e32 v2, v170, v144
	v_pk_add_f32 v[0:1], v[0:1], v[0:1] op_sel_hi:[0,1]
	v_mov_b32_e32 v51, v1
	v_pk_add_f32 v[0:1], v[48:49], v[50:51]
	v_exp_f32_e32 v48, v2
	v_pk_add_f32 v[0:1], v[0:1], v[0:1] op_sel_hi:[0,1]
	v_mov_b32_e32 v55, v1
	v_pk_add_f32 v[0:1], v[52:53], v[54:55]
	v_sub_f32_e32 v2, v169, v144
	v_pk_add_f32 v[0:1], v[0:1], v[0:1] op_sel_hi:[0,1]
	v_mov_b32_e32 v11, v1
	v_pk_add_f32 v[0:1], v[8:9], v[10:11]
	v_sub_f32_e32 v3, v155, v144
	v_pk_add_f32 v[14:15], v[0:1], v[0:1] op_sel_hi:[0,1]
	v_exp_f32_e32 v14, v2
	v_sub_f32_e32 v2, v158, v144
	v_exp_f32_e32 v2, v2
	v_exp_f32_e32 v3, v3
	v_add_u32_e32 v53, 0x9000, v143
	ds_read2_b64 v[4:7], v53 offset1:2
	v_sub_f32_e32 v0, v172, v144
	v_add_f32_e32 v51, v2, v3
	v_cvt_pk_bf16_f32 v2, v2, v3
	v_sub_f32_e32 v3, v154, v144
	v_sub_f32_e32 v1, v171, v144
	v_exp_f32_e32 v50, v3
	v_sub_f32_e32 v3, v153, v144
	v_exp_f32_e32 v0, v0
	v_exp_f32_e32 v1, v1
	v_exp_f32_e32 v52, v3
	ds_read2_b64 v[10:13], v57 offset0:32 offset1:34
	v_sub_f32_e32 v3, v152, v144
	v_exp_f32_e32 v8, v3
	v_sub_f32_e32 v3, v151, v144
	v_add_f32_e32 v49, v0, v1
	v_cvt_pk_bf16_f32 v0, v0, v1
	v_cvt_pk_bf16_f32 v1, v48, v14
	v_exp_f32_e32 v9, v3
	v_cvt_pk_bf16_f32 v3, v50, v52
	v_add_f32_e32 v55, v8, v9
	s_waitcnt lgkmcnt(1)
	v_mfma_f32_32x32x16_bf16 v[16:31], v[4:7], v[0:3], v[16:31]
	v_sub_f32_e32 v4, v148, v144
	v_exp_f32_e32 v59, v4
	v_sub_f32_e32 v4, v147, v144
	v_exp_f32_e32 v60, v4
	ds_read2_b64 v[4:7], v53 offset0:4 offset1:6
	v_cvt_pk_bf16_f32 v8, v8, v9
	v_sub_f32_e32 v9, v150, v144
	v_exp_f32_e32 v54, v9
	v_sub_f32_e32 v9, v149, v144
	v_exp_f32_e32 v56, v9
	v_sub_f32_e32 v9, v146, v144
	s_waitcnt lgkmcnt(1)
	v_mfma_f32_32x32x16_bf16 v[32:47], v[10:13], v[0:3], v[32:47]
	v_sub_f32_e32 v0, v145, v144
	v_exp_f32_e32 v12, v9
	v_exp_f32_e32 v58, v0
	v_cvt_pk_bf16_f32 v9, v54, v56
	v_cvt_pk_bf16_f32 v10, v59, v60
	ds_read2_b64 v[0:3], v57 offset0:36 offset1:38
	v_cvt_pk_bf16_f32 v11, v12, v58
	v_add_f32_e32 v13, v59, v60
	s_waitcnt lgkmcnt(1)
	v_mfma_f32_32x32x16_bf16 v[16:31], v[4:7], v[8:11], v[16:31]
	v_add_f32_e64 v4, v48, v14
	v_add_f32_e64 v5, v49, v15
	v_sub_f32_e32 v6, v123, v144
	v_pk_add_f32 v[4:5], v[4:5], v[4:5] op_sel_hi:[0,1]
	v_mov_b32_e32 v53, v5
	v_pk_add_f32 v[4:5], v[50:51], v[52:53]
	v_exp_f32_e32 v6, v6
	v_pk_add_f32 v[4:5], v[4:5], v[4:5] op_sel_hi:[0,1]
	v_mov_b32_e32 v57, v5
	v_pk_add_f32 v[4:5], v[54:55], v[56:57]
	s_waitcnt lgkmcnt(0)
	v_mfma_f32_32x32x16_bf16 v[32:47], v[0:3], v[8:11], v[32:47]
	v_pk_add_f32 v[4:5], v[4:5], v[4:5] op_sel_hi:[0,1]
	v_mov_b32_e32 v59, v5
	v_pk_add_f32 v[4:5], v[12:13], v[58:59]
	s_waitcnt vmcnt(0)
	v_mov_b64_e32 v[12:13], v[108:109]
	v_pk_add_f32 v[4:5], v[4:5], v[4:5] op_sel:[0,1] op_sel_hi:[1,0]
	v_mov_b64_e32 v[14:15], v[110:111]
	v_mov_b32_e32 v5, v4
	s_nop 1
	v_permlane32_swap_b32_e32 v4, v5
	v_add_f32_e32 v4, v4, v5
	v_add_f32_e32 v4, v6, v4
	v_div_scale_f32 v5, s[20:21], v4, v4, 1.0
	v_rcp_f32_e32 v6, v5
	s_nop 0
	v_fma_f32 v0, -v5, v6, 1.0
	v_fmac_f32_e32 v6, v0, v6
	v_div_scale_f32 v0, vcc, 1.0, v4, 1.0
	v_mul_f32_e32 v1, v0, v6
	v_fma_f32 v2, -v5, v1, v0
	v_fmac_f32_e32 v1, v2, v6
	v_fma_f32 v0, -v5, v1, v0
	v_div_fmas_f32 v0, v0, v6, v1
	v_div_fixup_f32 v0, v0, v4, 1.0
	v_lshl_add_u64 v[2:3], s[18:19], 1, v[126:127]
	v_mbcnt_lo_u32_b32 v238, -1, 0
	v_mbcnt_hi_u32_b32 v238, -1, v238
	v_lshrrev_b32_e32 v238, 5, v238
	v_lshlrev_b32_e32 v238, 3, v238
	v_mov_b32_e32 v239, 0
	v_lshl_add_u64 v[2:3], v[2:3], 0, v[238:239]
	v_pk_mul_f32 v[240:241], v[32:33], v[0:1] op_sel_hi:[1,0]
	v_pk_mul_f32 v[242:243], v[34:35], v[0:1] op_sel_hi:[1,0]
	v_cvt_pk_bf16_f32 v244, v240, v241
	v_cvt_pk_bf16_f32 v245, v242, v243
	v_pk_mul_f32 v[240:241], v[36:37], v[0:1] op_sel_hi:[1,0]
	v_pk_mul_f32 v[242:243], v[38:39], v[0:1] op_sel_hi:[1,0]
	v_cvt_pk_bf16_f32 v246, v240, v241
	v_cvt_pk_bf16_f32 v247, v242, v243
	v_pk_mul_f32 v[240:241], v[40:41], v[0:1] op_sel_hi:[1,0]
	v_pk_mul_f32 v[242:243], v[42:43], v[0:1] op_sel_hi:[1,0]
	v_cvt_pk_bf16_f32 v248, v240, v241
	v_cvt_pk_bf16_f32 v249, v242, v243
	v_pk_mul_f32 v[240:241], v[44:45], v[0:1] op_sel_hi:[1,0]
	v_pk_mul_f32 v[242:243], v[46:47], v[0:1] op_sel_hi:[1,0]
	v_cvt_pk_bf16_f32 v250, v240, v241
	v_cvt_pk_bf16_f32 v251, v242, v243
	v_pk_mul_f32 v[240:241], v[16:17], v[0:1] op_sel_hi:[1,0]
	v_pk_mul_f32 v[242:243], v[18:19], v[0:1] op_sel_hi:[1,0]
	v_cvt_pk_bf16_f32 v4, v240, v241
	v_cvt_pk_bf16_f32 v5, v242, v243
	v_pk_mul_f32 v[240:241], v[20:21], v[0:1] op_sel_hi:[1,0]
	v_pk_mul_f32 v[242:243], v[22:23], v[0:1] op_sel_hi:[1,0]
	v_cvt_pk_bf16_f32 v6, v240, v241
	v_cvt_pk_bf16_f32 v7, v242, v243
	v_pk_mul_f32 v[240:241], v[24:25], v[0:1] op_sel_hi:[1,0]
	v_pk_mul_f32 v[242:243], v[26:27], v[0:1] op_sel_hi:[1,0]
	v_cvt_pk_bf16_f32 v8, v240, v241
	v_cvt_pk_bf16_f32 v9, v242, v243
	v_pk_mul_f32 v[240:241], v[28:29], v[0:1] op_sel_hi:[1,0]
	v_pk_mul_f32 v[242:243], v[30:31], v[0:1] op_sel_hi:[1,0]
	v_cvt_pk_bf16_f32 v10, v240, v241
	v_cvt_pk_bf16_f32 v11, v242, v243
	s_nop 1
	v_permlane32_swap_b32_e32 v4, v6
	v_permlane32_swap_b32_e32 v5, v7
	v_permlane32_swap_b32_e32 v8, v10
	v_permlane32_swap_b32_e32 v9, v11
	v_permlane32_swap_b32_e32 v244, v246
	v_permlane32_swap_b32_e32 v245, v247
	v_permlane32_swap_b32_e32 v248, v250
	v_permlane32_swap_b32_e32 v249, v251
	global_store_dwordx4 v[2:3], v[4:7], off
	global_store_dwordx4 v[2:3], v[8:11], off offset:32
	global_store_dwordx4 v[2:3], v[244:247], off offset:64
	global_store_dwordx4 v[2:3], v[248:251], off offset:96
	s_nop 1
	v_mov_b64_e32 v[4:5], v[96:97]
	v_mov_b64_e32 v[0:1], v[100:101]
	v_mov_b64_e32 v[8:9], v[104:105]
	v_mov_b64_e32 v[6:7], v[98:99]
	v_mov_b64_e32 v[2:3], v[102:103]
	v_mov_b64_e32 v[10:11], v[106:107]
	s_cbranch_scc1 .LBB0_158
